# conv row loop VALU body in packed f32 (pk_fma taps, pk silu, pk_mov history shift)
# speedup vs baseline: 1.0011x; 1.0011x over previous
; __device__ __forceinline__ unsigned cvt_pk_bf16(float lo, float hi) { unsigned r; asm("v_cvt_pk_bf16_f32 %0, %1, %2" : "=v"(r) : "v"(lo), "v"(hi)); return r; }
; __device__ __forceinline__ float siluf(float x) { return x * __builtin_amdgcn_rcpf(1.0f + __expf(-x)); }
; __device__ __forceinline__ void conv_phase(ArgsP a_) { const ArgsP a = a_;
;     ...
;         for (int j = 0; j < nrow; ++j) {
;             const u32x4 x = *(const u32x4*)(XBC + (size_t)(row0 + j) * 4096 + col); float cur[8];
;             cur[0] = __uint_as_float(x.x << 16); cur[1] = __uint_as_float(x.x & 0xffff0000u); cur[2] = __uint_as_float(x.y << 16); cur[3] = __uint_as_float(x.y & 0xffff0000u);
;             cur[4] = __uint_as_float(x.z << 16); cur[5] = __uint_as_float(x.z & 0xffff0000u); cur[6] = __uint_as_float(x.w << 16); cur[7] = __uint_as_float(x.w & 0xffff0000u);
;             float y[8];
; #pragma unroll
;             for (int e = 0; e < 8; ++e) { y[e] = siluf(bs[e] + w[0][e] * r[0][e] + w[1][e] * r[1][e] + w[2][e] * r[2][e] + w[3][e] * cur[e]); r[0][e] = r[1][e]; r[1][e] = r[2][e]; r[2][e] = cur[e]; }
;             *(u32x4*)(XC + (size_t)(row0 + j) * 4096 + col) = (u32x4){cvt_pk_bf16(y[0], y[1]), cvt_pk_bf16(y[2], y[3]), cvt_pk_bf16(y[4], y[5]), cvt_pk_bf16(y[6], y[7])};
;         }
.LBB0_54:
	s_or_b64 exec, exec, s[34:35]
	v_lshl_add_u64 v[80:81], s[24:25], 0, v[16:17]
	s_waitcnt vmcnt(0)
	v_mov_b32_e32 v82, v52
	s_waitcnt vmcnt(4)
	v_mov_b32_e32 v83, v14
	v_mov_b32_e32 v14, v53
	s_waitcnt vmcnt(3)
	v_mov_b32_e32 v52, v56
	v_mov_b32_e32 v53, v6
	v_mov_b32_e32 v6, v57
	v_mov_b32_e32 v56, v50
	v_mov_b32_e32 v57, v12
	v_mov_b32_e32 v12, v51
	v_mov_b32_e32 v50, v54
	v_mov_b32_e32 v51, v4
	v_mov_b32_e32 v4, v55
	v_mov_b32_e32 v54, v44
	v_mov_b32_e32 v55, v10
	v_mov_b32_e32 v10, v45
	s_waitcnt vmcnt(1)
	v_mov_b32_e32 v44, v48
	v_mov_b32_e32 v45, v2
	v_mov_b32_e32 v2, v49
	v_mov_b32_e32 v48, v42
	v_mov_b32_e32 v49, v8
	v_mov_b32_e32 v8, v43
	v_mov_b32_e32 v42, v46
	v_mov_b32_e32 v43, v0
	v_mov_b32_e32 v0, v47
	v_mov_b32_e32 v100, v22
	v_mov_b32_e32 v101, 0
	v_mov_b32_e32 v102, v23
	v_mov_b32_e32 v103, 0
	v_mov_b32_e32 v104, v24
	v_mov_b32_e32 v105, 0
	v_mov_b32_e32 v106, v25
	v_mov_b32_e32 v107, 0
	v_mov_b32_e32 v108, v18
	v_mov_b32_e32 v109, 0
	v_mov_b32_e32 v110, v19
	v_mov_b32_e32 v111, 0
	v_mov_b32_e32 v112, v20
	v_mov_b32_e32 v113, 0
	v_mov_b32_e32 v114, v21
	v_mov_b32_e32 v115, 0
	v_mov_b32_e32 v98, 0xbfb8aa3b
	v_mov_b32_e32 v99, 0xbfb8aa3b
	s_mov_b64 s[34:35], 0
	v_ashrrev_i32_e32 v61, 31, v60
	v_lshlrev_b64 v[212:213], 13, v[60:61]
	v_lshl_add_u64 v[212:213], v[62:63], 0, v[212:213]
	global_load_dwordx4 v[202:205], v[212:213], off
	s_waitcnt vmcnt(0)
.LBB0_55:
	v_ashrrev_i32_e32 v61, 31, v60
	v_lshlrev_b64 v[46:47], 13, v[60:61]
	v_add_u32_e32 v212, 1, v60
	v_ashrrev_i32_e32 v213, 31, v212
	v_lshlrev_b64 v[212:213], 13, v[212:213]
	v_lshl_add_u64 v[212:213], v[62:63], 0, v[212:213]
	s_waitcnt vmcnt(1)
	v_mov_b32_e32 v86, v202
	v_mov_b32_e32 v87, v203
	v_mov_b32_e32 v88, v204
	v_mov_b32_e32 v89, v205
	global_load_dwordx4 v[202:205], v[212:213], off
	v_add_u32_e32 v84, -1, v84
	v_cmp_eq_u32_e32 vcc, 0, v84
	v_lshl_add_u64 v[46:47], v[80:81], 0, v[46:47]
	v_add_u32_e32 v60, 1, v60
	s_or_b64 s[34:35], vcc, s[34:35]
	v_lshlrev_b32_e32 v35, 16, v86
	v_and_b32_e32 v73, 0xffff0000, v86
	v_lshlrev_b32_e32 v37, 16, v87
	v_and_b32_e32 v75, 0xffff0000, v87
	v_lshlrev_b32_e32 v39, 16, v88
	v_and_b32_e32 v77, 0xffff0000, v88
	v_lshlrev_b32_e32 v41, 16, v89
	v_and_b32_e32 v79, 0xffff0000, v89
	v_pk_fma_f32 v[116:117], v[42:43], v[26:27], v[100:101]
	v_pk_fma_f32 v[118:119], v[0:1], v[64:65], v[102:103]
	v_pk_fma_f32 v[120:121], v[44:45], v[28:29], v[104:105]
	v_pk_fma_f32 v[122:123], v[2:3], v[66:67], v[106:107]
	v_pk_fma_f32 v[124:125], v[50:51], v[30:31], v[108:109]
	v_pk_fma_f32 v[126:127], v[4:5], v[68:69], v[110:111]
	v_pk_fma_f32 v[128:129], v[52:53], v[32:33], v[112:113]
	v_pk_fma_f32 v[130:131], v[6:7], v[70:71], v[114:115]
	v_pk_fma_f32 v[116:117], v[48:49], v[34:35], v[116:117]
	v_pk_fma_f32 v[118:119], v[8:9], v[72:73], v[118:119]
	v_pk_fma_f32 v[120:121], v[54:55], v[36:37], v[120:121]
	v_pk_fma_f32 v[122:123], v[10:11], v[74:75], v[122:123]
	v_pk_fma_f32 v[124:125], v[56:57], v[38:39], v[124:125]
	v_pk_fma_f32 v[126:127], v[12:13], v[76:77], v[126:127]
	v_pk_fma_f32 v[128:129], v[82:83], v[40:41], v[128:129]
	v_pk_fma_f32 v[130:131], v[14:15], v[78:79], v[130:131]
	v_add_f32_e32 v132, v116, v117
	v_add_f32_e32 v133, v118, v119
	v_add_f32_e32 v134, v120, v121
	v_add_f32_e32 v135, v122, v123
	v_add_f32_e32 v136, v124, v125
	v_add_f32_e32 v137, v126, v127
	v_add_f32_e32 v138, v128, v129
	v_add_f32_e32 v139, v130, v131
	v_pk_mul_f32 v[90:91], v[132:133], v[98:99]
	v_pk_mul_f32 v[92:93], v[134:135], v[98:99]
	v_pk_mul_f32 v[94:95], v[136:137], v[98:99]
	v_pk_mul_f32 v[96:97], v[138:139], v[98:99]
	v_exp_f32_e32 v90, v90
	v_exp_f32_e32 v91, v91
	v_exp_f32_e32 v92, v92
	v_exp_f32_e32 v93, v93
	v_exp_f32_e32 v94, v94
	v_exp_f32_e32 v95, v95
	v_exp_f32_e32 v96, v96
	v_exp_f32_e32 v97, v97
	v_pk_add_f32 v[90:91], v[90:91], 1.0 op_sel_hi:[1,0]
	v_pk_add_f32 v[92:93], v[92:93], 1.0 op_sel_hi:[1,0]
	v_pk_add_f32 v[94:95], v[94:95], 1.0 op_sel_hi:[1,0]
	v_pk_add_f32 v[96:97], v[96:97], 1.0 op_sel_hi:[1,0]
	v_rcp_f32_e32 v90, v90
	v_rcp_f32_e32 v91, v91
	v_rcp_f32_e32 v92, v92
	v_rcp_f32_e32 v93, v93
	v_rcp_f32_e32 v94, v94
	v_rcp_f32_e32 v95, v95
	v_rcp_f32_e32 v96, v96
	v_rcp_f32_e32 v97, v97
	v_pk_mul_f32 v[132:133], v[132:133], v[90:91]
	v_pk_mul_f32 v[134:135], v[134:135], v[92:93]
	v_pk_mul_f32 v[136:137], v[136:137], v[94:95]
	v_pk_mul_f32 v[138:139], v[138:139], v[96:97]
	v_pk_mov_b32 v[26:27], v[26:27], v[34:35] op_sel:[1,0]
	v_pk_mov_b32 v[64:65], v[64:65], v[72:73] op_sel:[1,0]
	v_pk_mov_b32 v[28:29], v[28:29], v[36:37] op_sel:[1,0]
	v_pk_mov_b32 v[66:67], v[66:67], v[74:75] op_sel:[1,0]
	v_pk_mov_b32 v[30:31], v[30:31], v[38:39] op_sel:[1,0]
	v_pk_mov_b32 v[68:69], v[68:69], v[76:77] op_sel:[1,0]
	v_pk_mov_b32 v[32:33], v[32:33], v[40:41] op_sel:[1,0]
	v_pk_mov_b32 v[70:71], v[70:71], v[78:79] op_sel:[1,0]
	v_cvt_pk_bf16_f32 v86, v132, v133
	v_cvt_pk_bf16_f32 v87, v134, v135
	v_cvt_pk_bf16_f32 v88, v136, v137
	v_cvt_pk_bf16_f32 v89, v138, v139
	v_mov_b32_e32 v34, v35
	v_mov_b32_e32 v72, v73
	v_mov_b32_e32 v36, v37
	v_mov_b32_e32 v74, v75
	v_mov_b32_e32 v38, v39
	v_mov_b32_e32 v76, v77
	v_mov_b32_e32 v40, v41
	v_mov_b32_e32 v78, v79
	global_store_dwordx4 v[46:47], v[86:89], off
	s_andn2_b64 exec, exec, s[34:35]
	s_cbranch_execnz .LBB0_55
	s_or_b64 exec, exec, s[34:35]
	v_readlane_b32 s34, v253, 4
	v_readlane_b32 s35, v253, 5
	s_nop 1
	v_lshl_add_u64 v[58:59], v[58:59], 0, s[34:35]
	s_mov_b64 s[34:35], 0x90fff
	v_cmp_lt_u64_e32 vcc, s[34:35], v[58:59]
	s_or_b64 s[26:27], vcc, s[26:27]
	s_andn2_b64 exec, exec, s[26:27]
	s_cbranch_execnz .LBB0_32
